# v98 + 3-panel hand-offs poll their three counters in one loop (three loads in flight)
# speedup vs baseline: 1.0009x; 1.0009x over previous
.Lpm_m0:
	global_load_dword v2, v0, s[2:3] sc1
	global_load_dword v7, v3, s[2:3] sc1
	global_load_dword v8, v4, s[2:3] sc1
	s_waitcnt vmcnt(0)
	v_min3_u32 v2, v2, v7, v8
	v_cmp_le_u32_e32 vcc, s100, v2
	s_cbranch_vccnz .Lpe_m0
	s_sleep 1
	s_add_i32 s6, s6, 1
	s_cmp_lt_u32 s6, 0x100000
	s_cbranch_scc1 .Lpm_m0
